# DSA tile body: LDS fragment reads hoisted ahead of MFMAs with counted lgkmcnt; batched indexer scores with permlane16 swap
# speedup vs baseline: 1.0396x; 1.0171x over previous
; #define GAS __attribute__((address_space(1)))
; __device__ __forceinline__ f32x4 mfma16(bf16x8 a, bf16x8 b, f32x4 c) { return __builtin_amdgcn_mfma_f32_16x16x32_bf16(a, b, c, 0, 0, 0); }
; __device__ __forceinline__ void indexer_unit(const Args& a, LAS unsigned char* lds, LAS unsigned long long* maskl, int b, int qblk, int wave, int lane) {
;     ...
;     for (int kt = wave; kt < nkt; kt += 8) {
;         const int key = 16 * kt + fr;
;         const bf16x8 b0 = nb0, b1 = nb1;
;         { const int k2 = kt + 8 < nkt ? kt + 8 : kt; const GAS bf16* p = ikn + (rowb + 16 * k2 + fr) * 64 + 8 * fq; nb0 = *(const GAS bf16x8*)p; nb1 = *(const GAS bf16x8*)(p + 32); }
; #pragma unroll
;         for (int rt = 0; rt < 8; ++rt) {
;             f32x4 acc = {0.f, 0.f, 0.f, 0.f};
;             __builtin_amdgcn_s_setprio(1); acc = mfma16(af[rt][0], b0, acc); acc = mfma16(af[rt][1], b1, acc); __builtin_amdgcn_s_setprio(0);
;             float part = wv[rt][0] * fmaxf(acc[0], 0.f) + wv[rt][1] * fmaxf(acc[1], 0.f) + wv[rt][2] * fmaxf(acc[2], 0.f) + wv[rt][3] * fmaxf(acc[3], 0.f);
;             part += __shfl_xor(part, 16); part += 0.f;
;             if ((fq & 1) == 0) sc[(2 * rt + (fq >> 1)) * 2048 + key] = part;
;         }
;     }
.LBB0_1085:
	s_mov_b32 s11, s10
	s_add_i32 s10, s10, 8
	s_cmp_gt_u32 s10, s9
	s_cselect_b64 s[2:3], -1, 0
	s_and_b64 s[4:5], s[2:3], exec
	s_cselect_b32 s4, s11, s10
	v_lshl_add_u32 v74, s4, 4, v117
	v_mov_b32_e32 v75, v4
	v_lshlrev_b64 v[74:75], 7, v[74:75]
	v_lshl_add_u64 v[78:79], v[82:83], 0, v[74:75]
	global_load_dwordx4 v[74:77], v[78:79], off
	s_nop 0
	global_load_dwordx4 v[78:81], v[78:79], off offset:64
	s_setprio 1
	v_mfma_f32_16x16x32_bf16 v[128:131], v[0:3], v[70:73], 0
	v_mfma_f32_16x16x32_bf16 v[132:135], v[14:17], v[70:73], 0
	v_mfma_f32_16x16x32_bf16 v[136:139], v[18:21], v[70:73], 0
	v_mfma_f32_16x16x32_bf16 v[140:143], v[30:33], v[70:73], 0
	v_mfma_f32_16x16x32_bf16 v[144:147], v[34:37], v[70:73], 0
	v_mfma_f32_16x16x32_bf16 v[148:151], v[42:45], v[70:73], 0
	v_mfma_f32_16x16x32_bf16 v[152:155], v[54:57], v[70:73], 0
	v_mfma_f32_16x16x32_bf16 v[156:159], v[46:49], v[70:73], 0
	v_mfma_f32_16x16x32_bf16 v[128:131], v[6:9], v[66:69], v[128:131]
	v_mfma_f32_16x16x32_bf16 v[132:135], v[10:13], v[66:69], v[132:135]
	v_mfma_f32_16x16x32_bf16 v[136:139], v[22:25], v[66:69], v[136:139]
	v_mfma_f32_16x16x32_bf16 v[140:143], v[26:29], v[66:69], v[140:143]
	v_mfma_f32_16x16x32_bf16 v[144:147], v[38:41], v[66:69], v[144:147]
	v_mfma_f32_16x16x32_bf16 v[148:151], v[50:53], v[66:69], v[148:151]
	v_mfma_f32_16x16x32_bf16 v[152:155], v[58:61], v[66:69], v[152:155]
	v_mfma_f32_16x16x32_bf16 v[156:159], v[62:65], v[66:69], v[156:159]
	s_setprio 0
	s_nop 1
	v_max_f32_e32 v160, v128, v128
	v_max_f32_e32 v160, 0, v160
	v_max_f32_e32 v168, v129, v129
	v_max_f32_e32 v168, 0, v168
	v_mul_f32_e32 v168, v168, v86
	v_max_f32_e32 v161, v130, v130
	v_fmac_f32_e32 v168, v160, v85
	v_max_f32_e32 v161, 0, v161
	v_fmac_f32_e32 v168, v161, v87
	v_max_f32_e32 v161, v131, v131
	v_max_f32_e32 v161, 0, v161
	v_fmac_f32_e32 v168, v161, v88
	v_max_f32_e32 v160, v132, v132
	v_max_f32_e32 v160, 0, v160
	v_max_f32_e32 v169, v133, v133
	v_max_f32_e32 v169, 0, v169
	v_mul_f32_e32 v169, v169, v90
	v_max_f32_e32 v161, v134, v134
	v_fmac_f32_e32 v169, v160, v89
	v_max_f32_e32 v161, 0, v161
	v_fmac_f32_e32 v169, v161, v91
	v_max_f32_e32 v161, v135, v135
	v_max_f32_e32 v161, 0, v161
	v_fmac_f32_e32 v169, v161, v92
	v_max_f32_e32 v160, v136, v136
	v_max_f32_e32 v160, 0, v160
	v_max_f32_e32 v170, v137, v137
	v_max_f32_e32 v170, 0, v170
	v_mul_f32_e32 v170, v170, v94
	v_max_f32_e32 v161, v138, v138
	v_fmac_f32_e32 v170, v160, v93
	v_max_f32_e32 v161, 0, v161
	v_fmac_f32_e32 v170, v161, v95
	v_max_f32_e32 v161, v139, v139
	v_max_f32_e32 v161, 0, v161
	v_fmac_f32_e32 v170, v161, v96
	v_max_f32_e32 v160, v140, v140
	v_max_f32_e32 v160, 0, v160
	v_max_f32_e32 v171, v141, v141
	v_max_f32_e32 v171, 0, v171
	v_mul_f32_e32 v171, v171, v98
	v_max_f32_e32 v161, v142, v142
	v_fmac_f32_e32 v171, v160, v97
	v_max_f32_e32 v161, 0, v161
	v_fmac_f32_e32 v171, v161, v99
	v_max_f32_e32 v161, v143, v143
	v_max_f32_e32 v161, 0, v161
	v_fmac_f32_e32 v171, v161, v100
	v_max_f32_e32 v160, v144, v144
	v_max_f32_e32 v160, 0, v160
	v_max_f32_e32 v172, v145, v145
	v_max_f32_e32 v172, 0, v172
	v_mul_f32_e32 v172, v172, v102
	v_max_f32_e32 v161, v146, v146
	v_fmac_f32_e32 v172, v160, v101
	v_max_f32_e32 v161, 0, v161
	v_fmac_f32_e32 v172, v161, v103
	v_max_f32_e32 v161, v147, v147
	v_max_f32_e32 v161, 0, v161
	v_fmac_f32_e32 v172, v161, v104
	v_max_f32_e32 v160, v148, v148
	v_max_f32_e32 v160, 0, v160
	v_max_f32_e32 v173, v149, v149
	v_max_f32_e32 v173, 0, v173
	v_mul_f32_e32 v173, v173, v106
	v_max_f32_e32 v161, v150, v150
	v_fmac_f32_e32 v173, v160, v105
	v_max_f32_e32 v161, 0, v161
	v_fmac_f32_e32 v173, v161, v107
	v_max_f32_e32 v161, v151, v151
	v_max_f32_e32 v161, 0, v161
	v_fmac_f32_e32 v173, v161, v108
	v_max_f32_e32 v160, v152, v152
	v_max_f32_e32 v160, 0, v160
	v_max_f32_e32 v174, v153, v153
	v_max_f32_e32 v174, 0, v174
	v_mul_f32_e32 v174, v174, v110
	v_max_f32_e32 v161, v154, v154
	v_fmac_f32_e32 v174, v160, v109
	v_max_f32_e32 v161, 0, v161
	v_fmac_f32_e32 v174, v161, v111
	v_max_f32_e32 v161, v155, v155
	v_max_f32_e32 v161, 0, v161
	v_fmac_f32_e32 v174, v161, v112
	v_max_f32_e32 v160, v156, v156
	v_max_f32_e32 v160, 0, v160
	v_max_f32_e32 v175, v157, v157
	v_max_f32_e32 v175, 0, v175
	v_mul_f32_e32 v175, v175, v114
	v_max_f32_e32 v161, v158, v158
	v_fmac_f32_e32 v175, v160, v113
	v_max_f32_e32 v161, 0, v161
	v_fmac_f32_e32 v175, v161, v115
	v_max_f32_e32 v161, v159, v159
	v_max_f32_e32 v161, 0, v161
	v_fmac_f32_e32 v175, v161, v116
	v_mov_b32_e32 v120, v168
	v_mov_b32_e32 v121, v169
	v_mov_b32_e32 v122, v170
	v_mov_b32_e32 v123, v171
	v_mov_b32_e32 v124, v172
	v_mov_b32_e32 v125, v173
	v_mov_b32_e32 v126, v174
	v_mov_b32_e32 v127, v175
	v_permlane16_swap_b32_e32 v168, v120
	v_permlane16_swap_b32_e32 v169, v121
	v_permlane16_swap_b32_e32 v170, v122
	v_permlane16_swap_b32_e32 v171, v123
	v_permlane16_swap_b32_e32 v172, v124
	v_permlane16_swap_b32_e32 v173, v125
	v_permlane16_swap_b32_e32 v174, v126
	v_permlane16_swap_b32_e32 v175, v127
	v_add_f32_e32 v168, v168, v120
	v_add_f32_e32 v169, v169, v121
	v_add_f32_e32 v170, v170, v122
	v_add_f32_e32 v171, v171, v123
	v_add_f32_e32 v172, v172, v124
	v_add_f32_e32 v173, v173, v125
	v_add_f32_e32 v174, v174, v126
	v_add_f32_e32 v175, v175, v127
	v_add_f32_e32 v168, 0, v168
	v_add_f32_e32 v169, 0, v169
	v_add_f32_e32 v170, 0, v170
	v_add_f32_e32 v171, 0, v171
	v_add_f32_e32 v172, 0, v172
	v_add_f32_e32 v173, 0, v173
	v_add_f32_e32 v174, 0, v174
	v_add_f32_e32 v175, 0, v175
	v_add_u32_e32 v160, 0x10000, v119
	s_and_saveexec_b64 s[4:5], s[6:7]
	ds_write_b32 v119, v168
	ds_write_b32 v119, v169 offset:16384
	ds_write_b32 v119, v170 offset:32768
	ds_write_b32 v119, v171 offset:49152
	ds_write_b32 v160, v172
	ds_write_b32 v160, v173 offset:16384
	ds_write_b32 v160, v174 offset:32768
	ds_write_b32 v160, v175 offset:49152
	s_branch .LBB0_1084

; #define LAS __attribute__((address_space(3)))
; __device__ __forceinline__ unsigned pk2(float lo, float hi) { f32x2_t v = {lo, hi}; bf16x2_t b = __builtin_convertvector(v, bf16x2_t); return __builtin_bit_cast(unsigned, b); }
; __device__ __forceinline__ void dsa_unit32(const Args& a, LAS unsigned char* lds, const LAS unsigned long long* maskl, int b, int qb, int tid, int wave, int lane) {
;     ...
;     auto compute = [&](int buf, int kt) {
;         const unsigned long long mw = maskl[l31 * 32 + kt];
;         const LAS bf16* Ks = (const LAS bf16*)(lds + buf * STG); const LAS bf16* Vs = (const LAS bf16*)(lds + buf * STG + KBYTES);
;         f32x16 S2[2];
; #pragma unroll
;         for (int kh = 0; kh < 2; ++kh) {
; #pragma unroll
;             for (int i = 0; i < 16; ++i) S2[kh][i] = negB;
;             __builtin_amdgcn_s_setprio(1);
; #pragma unroll
;             for (int ks = 0; ks < 8; ++ks) S2[kh] = mfma32(*(const LAS bf16x8*)(Ks + (32 * kh + l31) * KS + 16 * ks + 8 * hi), qf[ks], S2[kh]);
;             __builtin_amdgcn_s_setprio(0);
;         }
; #pragma unroll
;         for (int kh = 0; kh < 2; ++kh) {
;             const unsigned mh = (unsigned)(mw >> (32 * kh + 4 * hi));
;             float p[16];
; #pragma unroll
;             for (int i = 0; i < 16; ++i) { const float e = __builtin_amdgcn_exp2f(S2[kh][i]);
;                 const int keep = __builtin_amdgcn_sbfe((int)mh, 8 * (i >> 2) + (i & 3), 1);
;                 p[i] = __builtin_bit_cast(float, __builtin_bit_cast(int, e) & keep); l += p[i]; }
;             u32x4 w0, w1;
;             w0.x = pk2(p[0], p[1]); w0.y = pk2(p[2], p[3]); w0.z = pk2(p[4], p[5]); w0.w = pk2(p[6], p[7]);
;             w1.x = pk2(p[8], p[9]); w1.y = pk2(p[10], p[11]); w1.z = pk2(p[12], p[13]); w1.w = pk2(p[14], p[15]);
;             const bf16x8 pa = __builtin_bit_cast(bf16x8, w0), pb = __builtin_bit_cast(bf16x8, w1);
;             __builtin_amdgcn_s_setprio(1);
; #pragma unroll
;             for (int ct = 0; ct < 4; ++ct) {
;                 const LAS bf16* vr = Vs + (32 * ct + l31) * VS + 4 * hi + 32 * kh;
;                 O[ct] = mfma32(cat8(*(const LAS u32x2*)(vr), *(const LAS u32x2*)(vr + 8)), pa, O[ct]);
;                 O[ct] = mfma32(cat8(*(const LAS u32x2*)(vr + 16), *(const LAS u32x2*)(vr + 24)), pb, O[ct]);
;             }
;             __builtin_amdgcn_s_setprio(0);
;         }
;     };
.LBB0_1304:
	v_add_u32_e32 v207, -8, v206
	ds_read_b64 v[220:221], v207
	v_add_u32_e32 v207, v202, v180
	ds_read_b128 v[216:219], v207 offset:0
	ds_read_b128 v[228:231], v207 offset:32
	ds_read_b128 v[232:235], v207 offset:64
	ds_read_b128 v[236:239], v207 offset:96
	ds_read_b128 v[240:243], v207 offset:128
	ds_read_b128 v[244:247], v207 offset:160
	ds_read_b128 v[248:251], v207 offset:192
	ds_read_b128 v[222:225], v207 offset:224
	ds_read_b128 v[208:211], v207 offset:8704
	ds_read_b128 v[212:215], v207 offset:8736
	s_setprio 1
	s_waitcnt lgkmcnt(9)
	v_mfma_f32_32x32x16_bf16 v[102:117], v[216:219], v[126:129], v[70:85]
	ds_read_b128 v[216:219], v207 offset:8768
	s_waitcnt lgkmcnt(9)
	v_mfma_f32_32x32x16_bf16 v[102:117], v[228:231], v[0:3], v[102:117]
	ds_read_b128 v[228:231], v207 offset:8800
	s_waitcnt lgkmcnt(9)
	v_mfma_f32_32x32x16_bf16 v[102:117], v[232:235], v[118:121], v[102:117]
	ds_read_b128 v[232:235], v207 offset:8832
	s_waitcnt lgkmcnt(9)
	v_mfma_f32_32x32x16_bf16 v[102:117], v[236:239], v[122:125], v[102:117]
	ds_read_b128 v[236:239], v207 offset:8864
	s_waitcnt lgkmcnt(9)
	v_mfma_f32_32x32x16_bf16 v[102:117], v[240:243], v[130:133], v[102:117]
	ds_read_b128 v[240:243], v207 offset:8896
	s_waitcnt lgkmcnt(9)
	v_mfma_f32_32x32x16_bf16 v[102:117], v[244:247], v[134:137], v[102:117]
	ds_read_b128 v[244:247], v207 offset:8928
	s_waitcnt lgkmcnt(9)
	v_mfma_f32_32x32x16_bf16 v[102:117], v[248:251], v[138:141], v[102:117]
	s_waitcnt lgkmcnt(8)
	v_mfma_f32_32x32x16_bf16 v[102:117], v[222:225], v[142:145], v[102:117]
	s_waitcnt lgkmcnt(7)
	v_mfma_f32_32x32x16_bf16 v[86:101], v[208:211], v[126:129], v[70:85]
	s_waitcnt lgkmcnt(6)
	v_mfma_f32_32x32x16_bf16 v[86:101], v[212:215], v[0:3], v[86:101]
	s_waitcnt lgkmcnt(5)
	v_mfma_f32_32x32x16_bf16 v[86:101], v[216:219], v[118:121], v[86:101]
	v_add_u32_e32 v207, 17408, v203
	ds_read2_b64 v[248:251], v207 offset0:0 offset1:2
	ds_read2_b64 v[222:225], v207 offset0:4 offset1:6
	v_add_u32_e32 v207, 22272, v203
	ds_read2_b64 v[216:219], v207 offset0:0 offset1:2
	s_waitcnt lgkmcnt(7)
	v_mfma_f32_32x32x16_bf16 v[86:101], v[228:231], v[122:125], v[86:101]
	ds_read2_b64 v[228:231], v207 offset0:4 offset1:6
	s_waitcnt lgkmcnt(7)
	v_mfma_f32_32x32x16_bf16 v[86:101], v[232:235], v[130:133], v[86:101]
	v_add_u32_e32 v207, 27136, v203
	ds_read2_b64 v[232:235], v207 offset0:0 offset1:2
	s_waitcnt lgkmcnt(7)
	v_mfma_f32_32x32x16_bf16 v[86:101], v[236:239], v[134:137], v[86:101]
	ds_read2_b64 v[236:239], v207 offset0:4 offset1:6
	s_waitcnt lgkmcnt(7)
	v_mfma_f32_32x32x16_bf16 v[86:101], v[240:243], v[138:141], v[86:101]
	v_add_u32_e32 v207, 32000, v203
	ds_read2_b64 v[240:243], v207 offset0:0 offset1:2
	s_waitcnt lgkmcnt(7)
	v_mfma_f32_32x32x16_bf16 v[86:101], v[244:247], v[142:145], v[86:101]
	ds_read2_b64 v[244:247], v207 offset0:4 offset1:6
	s_setprio 0
	v_lshrrev_b64 v[208:209], v182, v[220:221]
	v_exp_f32_e32 v102, v102
	v_lshrrev_b32_e32 v209, v182, v220
	v_exp_f32_e32 v103, v103
	v_and_b32_e32 v209, 1, v209
	v_exp_f32_e32 v104, v104
	v_cmp_eq_u32_e32 vcc, 1, v209
	v_and_b32_e32 v209, 2, v208
	v_exp_f32_e32 v105, v105
	v_cndmask_b32_e32 v102, 0, v102, vcc
	v_cmp_ne_u32_e32 vcc, 0, v209
	v_and_b32_e32 v209, 4, v208
	v_exp_f32_e32 v106, v106
	v_cndmask_b32_e32 v103, 0, v103, vcc
	v_cmp_ne_u32_e32 vcc, 0, v209
	v_and_b32_e32 v209, 8, v208
	v_exp_f32_e32 v107, v107
	v_cndmask_b32_e32 v104, 0, v104, vcc
	v_cmp_ne_u32_e32 vcc, 0, v209
	v_and_b32_e32 v209, 0x100, v208
	v_exp_f32_e32 v108, v108
	v_cndmask_b32_e32 v105, 0, v105, vcc
	v_cmp_ne_u32_e32 vcc, 0, v209
	v_and_b32_e32 v209, 0x200, v208
	v_exp_f32_e32 v109, v109
	v_cndmask_b32_e32 v106, 0, v106, vcc
	v_cmp_ne_u32_e32 vcc, 0, v209
	v_and_b32_e32 v209, 0x400, v208
	v_exp_f32_e32 v110, v110
	v_cndmask_b32_e32 v107, 0, v107, vcc
	v_cmp_ne_u32_e32 vcc, 0, v209
	v_and_b32_e32 v209, 0x800, v208
	v_exp_f32_e32 v111, v111
	v_cndmask_b32_e32 v108, 0, v108, vcc
	v_cmp_ne_u32_e32 vcc, 0, v209
	v_and_b32_e32 v209, 0x10000, v208
	v_exp_f32_e32 v112, v112
	v_cndmask_b32_e32 v109, 0, v109, vcc
	v_cmp_ne_u32_e32 vcc, 0, v209
	v_and_b32_e32 v209, 0x20000, v208
	v_exp_f32_e32 v113, v113
	v_cndmask_b32_e32 v110, 0, v110, vcc
	v_cmp_ne_u32_e32 vcc, 0, v209
	v_and_b32_e32 v209, 0x40000, v208
	v_exp_f32_e32 v114, v114
	v_cndmask_b32_e32 v111, 0, v111, vcc
	v_cmp_ne_u32_e32 vcc, 0, v209
	v_and_b32_e32 v209, 0x80000, v208
	v_exp_f32_e32 v115, v115
	v_cndmask_b32_e32 v112, 0, v112, vcc
	v_cmp_ne_u32_e32 vcc, 0, v209
	v_and_b32_e32 v209, 0x1000000, v208
	v_exp_f32_e32 v116, v116
	v_cndmask_b32_e32 v113, 0, v113, vcc
	v_cmp_ne_u32_e32 vcc, 0, v209
	v_and_b32_e32 v209, 0x2000000, v208
	v_exp_f32_e32 v117, v117
	v_cndmask_b32_e32 v114, 0, v114, vcc
	v_cmp_ne_u32_e32 vcc, 0, v209
	v_and_b32_e32 v209, 0x4000000, v208
	v_and_b32_e32 v208, 0x8000000, v208
	v_cndmask_b32_e32 v115, 0, v115, vcc
	v_cmp_ne_u32_e32 vcc, 0, v209
	v_cvt_pk_bf16_f32 v209, v104, v105
	v_cvt_pk_bf16_f32 v210, v106, v107
	v_cndmask_b32_e32 v116, 0, v116, vcc
	v_cmp_ne_u32_e32 vcc, 0, v208
	v_cvt_pk_bf16_f32 v208, v102, v103
	v_cvt_pk_bf16_f32 v211, v108, v109
	v_cndmask_b32_e32 v117, 0, v117, vcc
	v_cvt_pk_bf16_f32 v212, v110, v111
	v_cvt_pk_bf16_f32 v213, v112, v113
	v_cvt_pk_bf16_f32 v214, v114, v115
	v_cvt_pk_bf16_f32 v215, v116, v117
	s_nop 1
	s_setprio 1
	s_waitcnt lgkmcnt(7)
; #define LAS __attribute__((address_space(3)))
; __device__ __forceinline__ unsigned pk2(float lo, float hi) { f32x2_t v = {lo, hi}; bf16x2_t b = __builtin_convertvector(v, bf16x2_t); return __builtin_bit_cast(unsigned, b); }
; __device__ __forceinline__ f32x16 mfma32(bf16x8 a, bf16x8 b, f32x16 c) { return __builtin_amdgcn_mfma_f32_32x32x16_bf16(a, b, c, 0, 0, 0); }
; __device__ __forceinline__ void dsa_unit32(const Args& a, LAS unsigned char* lds, const LAS unsigned long long* maskl, int b, int qb, int tid, int wave, int lane) {
;     ...
; #pragma unroll
;         for (int kh = 0; kh < 2; ++kh) {
;             const unsigned mh = (unsigned)(mw >> (32 * kh + 4 * hi));
;             float p[16];
; #pragma unroll
;             for (int i = 0; i < 16; ++i) { const float e = __builtin_amdgcn_exp2f(S2[kh][i]);
;                 const int keep = __builtin_amdgcn_sbfe((int)mh, 8 * (i >> 2) + (i & 3), 1);
;                 p[i] = __builtin_bit_cast(float, __builtin_bit_cast(int, e) & keep); l += p[i]; }
;             u32x4 w0, w1;
;             w0.x = pk2(p[0], p[1]); w0.y = pk2(p[2], p[3]); w0.z = pk2(p[4], p[5]); w0.w = pk2(p[6], p[7]);
;             w1.x = pk2(p[8], p[9]); w1.y = pk2(p[10], p[11]); w1.z = pk2(p[12], p[13]); w1.w = pk2(p[14], p[15]);
;             const bf16x8 pa = __builtin_bit_cast(bf16x8, w0), pb = __builtin_bit_cast(bf16x8, w1);
;             __builtin_amdgcn_s_setprio(1);
; #pragma unroll
;             for (int ct = 0; ct < 4; ++ct) {
;                 const LAS bf16* vr = Vs + (32 * ct + l31) * VS + 4 * hi + 32 * kh;
;                 O[ct] = mfma32(cat8(*(const LAS u32x2*)(vr), *(const LAS u32x2*)(vr + 8)), pa, O[ct]);
;                 O[ct] = mfma32(cat8(*(const LAS u32x2*)(vr + 16), *(const LAS u32x2*)(vr + 24)), pb, O[ct]);
;             }
;             __builtin_amdgcn_s_setprio(0);
;         }
;     };
	v_mfma_f32_32x32x16_bf16 v[54:69], v[248:251], v[208:211], v[54:69]
	v_add_u32_e32 v207, 17408, v203
	ds_read2_b64 v[248:251], v207 offset0:8 offset1:10
	s_waitcnt lgkmcnt(7)
	v_mfma_f32_32x32x16_bf16 v[54:69], v[222:225], v[212:215], v[54:69]
	ds_read2_b64 v[222:225], v207 offset0:12 offset1:14
	s_waitcnt lgkmcnt(7)
	v_mfma_f32_32x32x16_bf16 v[38:53], v[216:219], v[208:211], v[38:53]
	v_add_u32_e32 v207, 22272, v203
	ds_read2_b64 v[216:219], v207 offset0:8 offset1:10
	s_waitcnt lgkmcnt(7)
	v_mfma_f32_32x32x16_bf16 v[38:53], v[228:231], v[212:215], v[38:53]
	ds_read2_b64 v[228:231], v207 offset0:12 offset1:14
	s_waitcnt lgkmcnt(7)
	v_mfma_f32_32x32x16_bf16 v[22:37], v[232:235], v[208:211], v[22:37]
	v_add_u32_e32 v207, 27136, v203
	ds_read2_b64 v[232:235], v207 offset0:8 offset1:10
	s_waitcnt lgkmcnt(7)
	v_mfma_f32_32x32x16_bf16 v[22:37], v[236:239], v[212:215], v[22:37]
	ds_read2_b64 v[236:239], v207 offset0:12 offset1:14
	s_waitcnt lgkmcnt(7)
	v_mfma_f32_32x32x16_bf16 v[6:21], v[240:243], v[208:211], v[6:21]
	v_add_u32_e32 v207, 32000, v203
	ds_read2_b64 v[240:243], v207 offset0:8 offset1:10
	s_waitcnt lgkmcnt(7)
	v_mfma_f32_32x32x16_bf16 v[6:21], v[244:247], v[212:215], v[6:21]
	ds_read2_b64 v[244:247], v207 offset0:12 offset1:14
	s_setprio 0
	v_exp_f32_e32 v86, v86
	v_lshrrev_b64 v[208:209], v184, v[220:221]
	v_exp_f32_e32 v87, v87
	v_and_b32_e32 v209, 1, v208
	v_exp_f32_e32 v88, v88
	v_cmp_eq_u32_e32 vcc, 1, v209
	v_and_b32_e32 v209, 2, v208
	v_exp_f32_e32 v89, v89
	v_cndmask_b32_e32 v86, 0, v86, vcc
	v_cmp_ne_u32_e32 vcc, 0, v209
	v_and_b32_e32 v209, 4, v208
	v_exp_f32_e32 v90, v90
	v_cndmask_b32_e32 v87, 0, v87, vcc
	v_cmp_ne_u32_e32 vcc, 0, v209
	v_and_b32_e32 v209, 8, v208
	v_exp_f32_e32 v91, v91
	v_cndmask_b32_e32 v88, 0, v88, vcc
	v_cmp_ne_u32_e32 vcc, 0, v209
	v_and_b32_e32 v209, 0x100, v208
	v_exp_f32_e32 v92, v92
	v_cndmask_b32_e32 v89, 0, v89, vcc
	v_cmp_ne_u32_e32 vcc, 0, v209
	v_and_b32_e32 v209, 0x200, v208
	v_exp_f32_e32 v93, v93
	v_cndmask_b32_e32 v90, 0, v90, vcc
	v_cmp_ne_u32_e32 vcc, 0, v209
	v_and_b32_e32 v209, 0x400, v208
	v_exp_f32_e32 v94, v94
	v_cndmask_b32_e32 v91, 0, v91, vcc
	v_cmp_ne_u32_e32 vcc, 0, v209
	v_and_b32_e32 v209, 0x800, v208
	v_exp_f32_e32 v95, v95
	v_cndmask_b32_e32 v92, 0, v92, vcc
	v_cmp_ne_u32_e32 vcc, 0, v209
	v_and_b32_e32 v209, 0x10000, v208
	v_exp_f32_e32 v96, v96
	v_cndmask_b32_e32 v93, 0, v93, vcc
	v_cmp_ne_u32_e32 vcc, 0, v209
	v_and_b32_e32 v209, 0x20000, v208
	v_exp_f32_e32 v97, v97
	v_cndmask_b32_e32 v94, 0, v94, vcc
	v_cmp_ne_u32_e32 vcc, 0, v209
	v_and_b32_e32 v209, 0x40000, v208
	v_exp_f32_e32 v98, v98
	v_cndmask_b32_e32 v95, 0, v95, vcc
	v_cmp_ne_u32_e32 vcc, 0, v209
	v_and_b32_e32 v209, 0x80000, v208
	v_exp_f32_e32 v99, v99
	v_cndmask_b32_e32 v96, 0, v96, vcc
	v_cmp_ne_u32_e32 vcc, 0, v209
	v_and_b32_e32 v209, 0x1000000, v208
	v_exp_f32_e32 v100, v100
	v_cndmask_b32_e32 v97, 0, v97, vcc
	v_cmp_ne_u32_e32 vcc, 0, v209
	v_and_b32_e32 v209, 0x2000000, v208
	v_exp_f32_e32 v101, v101
	v_cndmask_b32_e32 v98, 0, v98, vcc
	v_cmp_ne_u32_e32 vcc, 0, v209
	v_and_b32_e32 v209, 0x4000000, v208
	v_and_b32_e32 v208, 0x8000000, v208
	v_cndmask_b32_e32 v99, 0, v99, vcc
	v_cmp_ne_u32_e32 vcc, 0, v209
	v_cvt_pk_bf16_f32 v209, v88, v89
	v_cvt_pk_bf16_f32 v210, v90, v91
	v_cndmask_b32_e32 v100, 0, v100, vcc
	v_cmp_ne_u32_e32 vcc, 0, v208
	v_cvt_pk_bf16_f32 v208, v86, v87
	v_cvt_pk_bf16_f32 v211, v92, v93
	v_cndmask_b32_e32 v101, 0, v101, vcc
	v_cvt_pk_bf16_f32 v212, v94, v95
	v_cvt_pk_bf16_f32 v213, v96, v97
	v_cvt_pk_bf16_f32 v214, v98, v99
	v_cvt_pk_bf16_f32 v215, v100, v101
	s_nop 1
	s_setprio 1
	s_waitcnt lgkmcnt(7)
	v_mfma_f32_32x32x16_bf16 v[54:69], v[248:251], v[208:211], v[54:69]
	s_waitcnt lgkmcnt(6)
	v_mfma_f32_32x32x16_bf16 v[54:69], v[222:225], v[212:215], v[54:69]
	s_waitcnt lgkmcnt(5)
	v_mfma_f32_32x32x16_bf16 v[38:53], v[216:219], v[208:211], v[38:53]
	s_waitcnt lgkmcnt(4)
	v_mfma_f32_32x32x16_bf16 v[38:53], v[228:231], v[212:215], v[38:53]
	s_waitcnt lgkmcnt(3)
	v_mfma_f32_32x32x16_bf16 v[22:37], v[232:235], v[208:211], v[22:37]
	s_waitcnt lgkmcnt(2)
	v_mfma_f32_32x32x16_bf16 v[22:37], v[236:239], v[212:215], v[22:37]
	s_waitcnt lgkmcnt(1)
	v_mfma_f32_32x32x16_bf16 v[6:21], v[240:243], v[208:211], v[6:21]
	s_waitcnt lgkmcnt(0)
	v_mfma_f32_32x32x16_bf16 v[6:21], v[244:247], v[212:215], v[6:21]
	s_setprio 0
	s_add_i32 s7, s5, -2
	s_cmp_lt_u32 s7, s4
	s_cselect_b64 s[2:3], -1, 0
	s_cmp_ge_u32 s7, s4
	s_cbranch_scc1 .LBB0_1306
	s_mov_b32 s7, 0xd400
	v_add3_u32 v208, v195, v197, s7
	s_waitcnt vmcnt(3)
	ds_write_b128 v196, v[162:165] offset:36864
	s_waitcnt vmcnt(1)
	ds_write2_b64 v208, v[170:171], v[172:173] offset1:1
	ds_write_b128 v199, v[166:169] offset:36864
	v_add3_u32 v208, v195, v200, s7
	s_waitcnt vmcnt(0)
	ds_write2_b64 v208, v[174:175], v[176:177] offset1:1

; #define LAS __attribute__((address_space(3)))
; __device__ __forceinline__ unsigned pk2(float lo, float hi) { f32x2_t v = {lo, hi}; bf16x2_t b = __builtin_convertvector(v, bf16x2_t); return __builtin_bit_cast(unsigned, b); }
; __device__ __forceinline__ void dsa_unit32(const Args& a, LAS unsigned char* lds, const LAS unsigned long long* maskl, int b, int qb, int tid, int wave, int lane) {
;     ...
;     auto compute = [&](int buf, int kt) {
;         const unsigned long long mw = maskl[l31 * 32 + kt];
;         const LAS bf16* Ks = (const LAS bf16*)(lds + buf * STG); const LAS bf16* Vs = (const LAS bf16*)(lds + buf * STG + KBYTES);
;         f32x16 S2[2];
; #pragma unroll
;         for (int kh = 0; kh < 2; ++kh) {
; #pragma unroll
;             for (int i = 0; i < 16; ++i) S2[kh][i] = negB;
;             __builtin_amdgcn_s_setprio(1);
; #pragma unroll
;             for (int ks = 0; ks < 8; ++ks) S2[kh] = mfma32(*(const LAS bf16x8*)(Ks + (32 * kh + l31) * KS + 16 * ks + 8 * hi), qf[ks], S2[kh]);
;             __builtin_amdgcn_s_setprio(0);
;         }
; #pragma unroll
;         for (int kh = 0; kh < 2; ++kh) {
;             const unsigned mh = (unsigned)(mw >> (32 * kh + 4 * hi));
;             float p[16];
; #pragma unroll
;             for (int i = 0; i < 16; ++i) { const float e = __builtin_amdgcn_exp2f(S2[kh][i]);
;                 const int keep = __builtin_amdgcn_sbfe((int)mh, 8 * (i >> 2) + (i & 3), 1);
;                 p[i] = __builtin_bit_cast(float, __builtin_bit_cast(int, e) & keep); l += p[i]; }
;             u32x4 w0, w1;
;             w0.x = pk2(p[0], p[1]); w0.y = pk2(p[2], p[3]); w0.z = pk2(p[4], p[5]); w0.w = pk2(p[6], p[7]);
;             w1.x = pk2(p[8], p[9]); w1.y = pk2(p[10], p[11]); w1.z = pk2(p[12], p[13]); w1.w = pk2(p[14], p[15]);
;             const bf16x8 pa = __builtin_bit_cast(bf16x8, w0), pb = __builtin_bit_cast(bf16x8, w1);
;             __builtin_amdgcn_s_setprio(1);
; #pragma unroll
;             for (int ct = 0; ct < 4; ++ct) {
;                 const LAS bf16* vr = Vs + (32 * ct + l31) * VS + 4 * hi + 32 * kh;
;                 O[ct] = mfma32(cat8(*(const LAS u32x2*)(vr), *(const LAS u32x2*)(vr + 8)), pa, O[ct]);
;                 O[ct] = mfma32(cat8(*(const LAS u32x2*)(vr + 16), *(const LAS u32x2*)(vr + 24)), pb, O[ct]);
;             }
;             __builtin_amdgcn_s_setprio(0);
;         }
;     };
.LBB0_1309:
	ds_read_b64 v[220:221], v206
	v_add_u32_e32 v207, v202, v180
	ds_read_b128 v[216:219], v207 offset:36864
	ds_read_b128 v[228:231], v207 offset:36896
	ds_read_b128 v[232:235], v207 offset:36928
	ds_read_b128 v[236:239], v207 offset:36960
	ds_read_b128 v[240:243], v207 offset:36992
	ds_read_b128 v[244:247], v207 offset:37024
	ds_read_b128 v[248:251], v207 offset:37056
	ds_read_b128 v[222:225], v207 offset:37088
	ds_read_b128 v[208:211], v207 offset:45568
	ds_read_b128 v[212:215], v207 offset:45600
	s_setprio 1
	s_waitcnt lgkmcnt(9)
	v_mfma_f32_32x32x16_bf16 v[102:117], v[216:219], v[126:129], v[70:85]
	ds_read_b128 v[216:219], v207 offset:45632
	s_waitcnt lgkmcnt(9)
	v_mfma_f32_32x32x16_bf16 v[102:117], v[228:231], v[0:3], v[102:117]
	ds_read_b128 v[228:231], v207 offset:45664
	s_waitcnt lgkmcnt(9)
	v_mfma_f32_32x32x16_bf16 v[102:117], v[232:235], v[118:121], v[102:117]
	ds_read_b128 v[232:235], v207 offset:45696
	s_waitcnt lgkmcnt(9)
	v_mfma_f32_32x32x16_bf16 v[102:117], v[236:239], v[122:125], v[102:117]
	ds_read_b128 v[236:239], v207 offset:45728
	s_waitcnt lgkmcnt(9)
	v_mfma_f32_32x32x16_bf16 v[102:117], v[240:243], v[130:133], v[102:117]
	ds_read_b128 v[240:243], v207 offset:45760
	s_waitcnt lgkmcnt(9)
	v_mfma_f32_32x32x16_bf16 v[102:117], v[244:247], v[134:137], v[102:117]
	ds_read_b128 v[244:247], v207 offset:45792
	s_waitcnt lgkmcnt(9)
	v_mfma_f32_32x32x16_bf16 v[102:117], v[248:251], v[138:141], v[102:117]
	s_waitcnt lgkmcnt(8)
	v_mfma_f32_32x32x16_bf16 v[102:117], v[222:225], v[142:145], v[102:117]
	s_waitcnt lgkmcnt(7)
	v_mfma_f32_32x32x16_bf16 v[86:101], v[208:211], v[126:129], v[70:85]
	s_waitcnt lgkmcnt(6)
	v_mfma_f32_32x32x16_bf16 v[86:101], v[212:215], v[0:3], v[86:101]
	s_waitcnt lgkmcnt(5)
	v_mfma_f32_32x32x16_bf16 v[86:101], v[216:219], v[118:121], v[86:101]
	ds_read2_b64 v[248:251], v204 offset0:0 offset1:2
	ds_read2_b64 v[222:225], v204 offset0:4 offset1:6
	v_add_u32_e32 v207, 4864, v204
	ds_read2_b64 v[216:219], v207 offset0:0 offset1:2
	s_waitcnt lgkmcnt(7)
	v_mfma_f32_32x32x16_bf16 v[86:101], v[228:231], v[122:125], v[86:101]
	ds_read2_b64 v[228:231], v207 offset0:4 offset1:6
	s_waitcnt lgkmcnt(7)
	v_mfma_f32_32x32x16_bf16 v[86:101], v[232:235], v[130:133], v[86:101]
	v_add_u32_e32 v207, 9728, v204
	ds_read2_b64 v[232:235], v207 offset0:0 offset1:2
	s_waitcnt lgkmcnt(7)
	v_mfma_f32_32x32x16_bf16 v[86:101], v[236:239], v[134:137], v[86:101]
	ds_read2_b64 v[236:239], v207 offset0:4 offset1:6
	s_waitcnt lgkmcnt(7)
	v_mfma_f32_32x32x16_bf16 v[86:101], v[240:243], v[138:141], v[86:101]
	v_add_u32_e32 v207, 14592, v204
	ds_read2_b64 v[240:243], v207 offset0:0 offset1:2
	s_waitcnt lgkmcnt(7)
	v_mfma_f32_32x32x16_bf16 v[86:101], v[244:247], v[142:145], v[86:101]
	ds_read2_b64 v[244:247], v207 offset0:4 offset1:6
	s_setprio 0
	v_lshrrev_b64 v[208:209], v182, v[220:221]
	v_exp_f32_e32 v102, v102
	v_lshrrev_b32_e32 v209, v182, v220
	v_exp_f32_e32 v103, v103
	v_and_b32_e32 v209, 1, v209
	v_exp_f32_e32 v104, v104
	v_cmp_eq_u32_e32 vcc, 1, v209
	v_and_b32_e32 v209, 2, v208
	v_exp_f32_e32 v105, v105
	v_cndmask_b32_e32 v102, 0, v102, vcc
	v_cmp_ne_u32_e32 vcc, 0, v209
	v_and_b32_e32 v209, 4, v208
	v_exp_f32_e32 v106, v106
	v_cndmask_b32_e32 v103, 0, v103, vcc
	v_cmp_ne_u32_e32 vcc, 0, v209
	v_and_b32_e32 v209, 8, v208
	v_exp_f32_e32 v107, v107
	v_cndmask_b32_e32 v104, 0, v104, vcc
	v_cmp_ne_u32_e32 vcc, 0, v209
	v_and_b32_e32 v209, 0x100, v208
	v_exp_f32_e32 v108, v108
	v_cndmask_b32_e32 v105, 0, v105, vcc
	v_cmp_ne_u32_e32 vcc, 0, v209
	v_and_b32_e32 v209, 0x200, v208
	v_exp_f32_e32 v109, v109
	v_cndmask_b32_e32 v106, 0, v106, vcc
	v_cmp_ne_u32_e32 vcc, 0, v209
	v_and_b32_e32 v209, 0x400, v208
	v_exp_f32_e32 v110, v110
	v_cndmask_b32_e32 v107, 0, v107, vcc
	v_cmp_ne_u32_e32 vcc, 0, v209
	v_and_b32_e32 v209, 0x800, v208
	v_exp_f32_e32 v111, v111
	v_cndmask_b32_e32 v108, 0, v108, vcc
	v_cmp_ne_u32_e32 vcc, 0, v209
	v_and_b32_e32 v209, 0x10000, v208
	v_exp_f32_e32 v112, v112
	v_cndmask_b32_e32 v109, 0, v109, vcc
	v_cmp_ne_u32_e32 vcc, 0, v209
	v_and_b32_e32 v209, 0x20000, v208
	v_exp_f32_e32 v113, v113
	v_cndmask_b32_e32 v110, 0, v110, vcc
	v_cmp_ne_u32_e32 vcc, 0, v209
	v_and_b32_e32 v209, 0x40000, v208
	v_exp_f32_e32 v114, v114
	v_cndmask_b32_e32 v111, 0, v111, vcc
	v_cmp_ne_u32_e32 vcc, 0, v209
	v_and_b32_e32 v209, 0x80000, v208
	v_exp_f32_e32 v115, v115
	v_cndmask_b32_e32 v112, 0, v112, vcc
	v_cmp_ne_u32_e32 vcc, 0, v209
	v_and_b32_e32 v209, 0x1000000, v208
	v_exp_f32_e32 v116, v116
	v_cndmask_b32_e32 v113, 0, v113, vcc
	v_cmp_ne_u32_e32 vcc, 0, v209
	v_and_b32_e32 v209, 0x2000000, v208
	v_exp_f32_e32 v117, v117
	v_cndmask_b32_e32 v114, 0, v114, vcc
	v_cmp_ne_u32_e32 vcc, 0, v209
	v_and_b32_e32 v209, 0x4000000, v208
	v_and_b32_e32 v208, 0x8000000, v208
	v_cndmask_b32_e32 v115, 0, v115, vcc
	v_cmp_ne_u32_e32 vcc, 0, v209
	v_cvt_pk_bf16_f32 v209, v104, v105
	v_cvt_pk_bf16_f32 v210, v106, v107
	v_cndmask_b32_e32 v116, 0, v116, vcc
	v_cmp_ne_u32_e32 vcc, 0, v208
	v_cvt_pk_bf16_f32 v208, v102, v103
	v_cvt_pk_bf16_f32 v211, v108, v109
	v_cndmask_b32_e32 v117, 0, v117, vcc
	v_cvt_pk_bf16_f32 v212, v110, v111
	v_cvt_pk_bf16_f32 v213, v112, v113
	v_cvt_pk_bf16_f32 v214, v114, v115
	v_cvt_pk_bf16_f32 v215, v116, v117
	s_nop 1
	s_setprio 1
	s_waitcnt lgkmcnt(7)
; #define LAS __attribute__((address_space(3)))
; __device__ __forceinline__ unsigned pk2(float lo, float hi) { f32x2_t v = {lo, hi}; bf16x2_t b = __builtin_convertvector(v, bf16x2_t); return __builtin_bit_cast(unsigned, b); }
; __device__ __forceinline__ f32x16 mfma32(bf16x8 a, bf16x8 b, f32x16 c) { return __builtin_amdgcn_mfma_f32_32x32x16_bf16(a, b, c, 0, 0, 0); }
; __device__ __forceinline__ void dsa_unit32(const Args& a, LAS unsigned char* lds, const LAS unsigned long long* maskl, int b, int qb, int tid, int wave, int lane) {
;     ...
; #pragma unroll
;         for (int kh = 0; kh < 2; ++kh) {
;             const unsigned mh = (unsigned)(mw >> (32 * kh + 4 * hi));
;             float p[16];
; #pragma unroll
;             for (int i = 0; i < 16; ++i) { const float e = __builtin_amdgcn_exp2f(S2[kh][i]);
;                 const int keep = __builtin_amdgcn_sbfe((int)mh, 8 * (i >> 2) + (i & 3), 1);
;                 p[i] = __builtin_bit_cast(float, __builtin_bit_cast(int, e) & keep); l += p[i]; }
;             u32x4 w0, w1;
;             w0.x = pk2(p[0], p[1]); w0.y = pk2(p[2], p[3]); w0.z = pk2(p[4], p[5]); w0.w = pk2(p[6], p[7]);
;             w1.x = pk2(p[8], p[9]); w1.y = pk2(p[10], p[11]); w1.z = pk2(p[12], p[13]); w1.w = pk2(p[14], p[15]);
;             const bf16x8 pa = __builtin_bit_cast(bf16x8, w0), pb = __builtin_bit_cast(bf16x8, w1);
;             __builtin_amdgcn_s_setprio(1);
; #pragma unroll
;             for (int ct = 0; ct < 4; ++ct) {
;                 const LAS bf16* vr = Vs + (32 * ct + l31) * VS + 4 * hi + 32 * kh;
;                 O[ct] = mfma32(cat8(*(const LAS u32x2*)(vr), *(const LAS u32x2*)(vr + 8)), pa, O[ct]);
;                 O[ct] = mfma32(cat8(*(const LAS u32x2*)(vr + 16), *(const LAS u32x2*)(vr + 24)), pb, O[ct]);
;             }
;             __builtin_amdgcn_s_setprio(0);
;         }
;     };
	v_mfma_f32_32x32x16_bf16 v[54:69], v[248:251], v[208:211], v[54:69]
	ds_read2_b64 v[248:251], v204 offset0:8 offset1:10
	s_waitcnt lgkmcnt(7)
	v_mfma_f32_32x32x16_bf16 v[54:69], v[222:225], v[212:215], v[54:69]
	ds_read2_b64 v[222:225], v204 offset0:12 offset1:14
	s_waitcnt lgkmcnt(7)
	v_mfma_f32_32x32x16_bf16 v[38:53], v[216:219], v[208:211], v[38:53]
	v_add_u32_e32 v207, 4864, v204
	ds_read2_b64 v[216:219], v207 offset0:8 offset1:10
	s_waitcnt lgkmcnt(7)
	v_mfma_f32_32x32x16_bf16 v[38:53], v[228:231], v[212:215], v[38:53]
	ds_read2_b64 v[228:231], v207 offset0:12 offset1:14
	s_waitcnt lgkmcnt(7)
	v_mfma_f32_32x32x16_bf16 v[22:37], v[232:235], v[208:211], v[22:37]
	v_add_u32_e32 v207, 9728, v204
	ds_read2_b64 v[232:235], v207 offset0:8 offset1:10
	s_waitcnt lgkmcnt(7)
	v_mfma_f32_32x32x16_bf16 v[22:37], v[236:239], v[212:215], v[22:37]
	ds_read2_b64 v[236:239], v207 offset0:12 offset1:14
	s_waitcnt lgkmcnt(7)
	v_mfma_f32_32x32x16_bf16 v[6:21], v[240:243], v[208:211], v[6:21]
	v_add_u32_e32 v207, 14592, v204
	ds_read2_b64 v[240:243], v207 offset0:8 offset1:10
	s_waitcnt lgkmcnt(7)
	v_mfma_f32_32x32x16_bf16 v[6:21], v[244:247], v[212:215], v[6:21]
	ds_read2_b64 v[244:247], v207 offset0:12 offset1:14
	s_setprio 0
	v_exp_f32_e32 v86, v86
	v_lshrrev_b64 v[208:209], v184, v[220:221]
	v_exp_f32_e32 v87, v87
	v_and_b32_e32 v209, 1, v208
	v_exp_f32_e32 v88, v88
	v_cmp_eq_u32_e32 vcc, 1, v209
	v_and_b32_e32 v209, 2, v208
	v_exp_f32_e32 v89, v89
	v_cndmask_b32_e32 v86, 0, v86, vcc
	v_cmp_ne_u32_e32 vcc, 0, v209
	v_and_b32_e32 v209, 4, v208
	v_exp_f32_e32 v90, v90
	v_cndmask_b32_e32 v87, 0, v87, vcc
	v_cmp_ne_u32_e32 vcc, 0, v209
	v_and_b32_e32 v209, 8, v208
	v_exp_f32_e32 v91, v91
	v_cndmask_b32_e32 v88, 0, v88, vcc
	v_cmp_ne_u32_e32 vcc, 0, v209
	v_and_b32_e32 v209, 0x100, v208
	v_exp_f32_e32 v92, v92
	v_cndmask_b32_e32 v89, 0, v89, vcc
	v_cmp_ne_u32_e32 vcc, 0, v209
	v_and_b32_e32 v209, 0x200, v208
	v_exp_f32_e32 v93, v93
	v_cndmask_b32_e32 v90, 0, v90, vcc
	v_cmp_ne_u32_e32 vcc, 0, v209
	v_and_b32_e32 v209, 0x400, v208
	v_exp_f32_e32 v94, v94
	v_cndmask_b32_e32 v91, 0, v91, vcc
	v_cmp_ne_u32_e32 vcc, 0, v209
	v_and_b32_e32 v209, 0x800, v208
	v_exp_f32_e32 v95, v95
	v_cndmask_b32_e32 v92, 0, v92, vcc
	v_cmp_ne_u32_e32 vcc, 0, v209
	v_and_b32_e32 v209, 0x10000, v208
	v_exp_f32_e32 v96, v96
	v_cndmask_b32_e32 v93, 0, v93, vcc
	v_cmp_ne_u32_e32 vcc, 0, v209
	v_and_b32_e32 v209, 0x20000, v208
	v_exp_f32_e32 v97, v97
	v_cndmask_b32_e32 v94, 0, v94, vcc
	v_cmp_ne_u32_e32 vcc, 0, v209
	v_and_b32_e32 v209, 0x40000, v208
	v_exp_f32_e32 v98, v98
	v_cndmask_b32_e32 v95, 0, v95, vcc
	v_cmp_ne_u32_e32 vcc, 0, v209
	v_and_b32_e32 v209, 0x80000, v208
	v_exp_f32_e32 v99, v99
	v_cndmask_b32_e32 v96, 0, v96, vcc
	v_cmp_ne_u32_e32 vcc, 0, v209
	v_and_b32_e32 v209, 0x1000000, v208
	v_exp_f32_e32 v100, v100
	v_cndmask_b32_e32 v97, 0, v97, vcc
	v_cmp_ne_u32_e32 vcc, 0, v209
	v_and_b32_e32 v209, 0x2000000, v208
	v_exp_f32_e32 v101, v101
	v_cndmask_b32_e32 v98, 0, v98, vcc
	v_cmp_ne_u32_e32 vcc, 0, v209
	v_and_b32_e32 v209, 0x4000000, v208
	v_and_b32_e32 v208, 0x8000000, v208
	v_cndmask_b32_e32 v99, 0, v99, vcc
	v_cmp_ne_u32_e32 vcc, 0, v209
	v_cvt_pk_bf16_f32 v209, v88, v89
	v_cvt_pk_bf16_f32 v210, v90, v91
	v_cndmask_b32_e32 v100, 0, v100, vcc
	v_cmp_ne_u32_e32 vcc, 0, v208
	v_cvt_pk_bf16_f32 v208, v86, v87
	v_cvt_pk_bf16_f32 v211, v92, v93
	v_cndmask_b32_e32 v101, 0, v101, vcc
	v_cvt_pk_bf16_f32 v212, v94, v95
	v_cvt_pk_bf16_f32 v213, v96, v97
	v_cvt_pk_bf16_f32 v214, v98, v99
	v_cvt_pk_bf16_f32 v215, v100, v101
	s_nop 1
	s_setprio 1
	s_waitcnt lgkmcnt(7)
	v_mfma_f32_32x32x16_bf16 v[54:69], v[248:251], v[208:211], v[54:69]
	s_waitcnt lgkmcnt(6)
	v_mfma_f32_32x32x16_bf16 v[54:69], v[222:225], v[212:215], v[54:69]
	s_waitcnt lgkmcnt(5)
	v_mfma_f32_32x32x16_bf16 v[38:53], v[216:219], v[208:211], v[38:53]
	s_waitcnt lgkmcnt(4)
	v_mfma_f32_32x32x16_bf16 v[38:53], v[228:231], v[212:215], v[38:53]
	s_waitcnt lgkmcnt(3)
	v_mfma_f32_32x32x16_bf16 v[22:37], v[232:235], v[208:211], v[22:37]
	s_waitcnt lgkmcnt(2)
	v_mfma_f32_32x32x16_bf16 v[22:37], v[236:239], v[212:215], v[22:37]
	s_waitcnt lgkmcnt(1)
	v_mfma_f32_32x32x16_bf16 v[6:21], v[240:243], v[208:211], v[6:21]
	s_waitcnt lgkmcnt(0)
	v_mfma_f32_32x32x16_bf16 v[6:21], v[244:247], v[212:215], v[6:21]
	s_setprio 0
	s_andn2_b64 vcc, exec, s[0:1]
	s_cbranch_vccnz .LBB0_1301
	s_waitcnt vmcnt(3)
	ds_write_b128 v196, v[146:149]
	s_waitcnt vmcnt(1)
	ds_write2_b64 v198, v[154:155], v[156:157] offset1:1
	ds_write_b128 v199, v[150:153]
	s_waitcnt vmcnt(0)
	ds_write2_b64 v201, v[158:159], v[160:161] offset1:1
	s_branch .LBB0_1301
